# ph3 row loop: wave-wide sum of the two row norms via v_permlane32/16_swap + DPP adds (same xor butterfly order) instead of six ds_bpermute LDS round trips
# baseline (speedup 1.0000x reference)
; #define GAS __attribute__((address_space(1)))
; DI unsigned pk2(float a, float b) { f32x2 v = {a, b}; bf2_t r = __builtin_convertvector(v, bf2_t); return __builtin_bit_cast(unsigned, r); }
; DI float bflo(unsigned w) { return __uint_as_float(w << 16); }
; DI float bfhi(unsigned w) { return __uint_as_float(w & 0xffff0000u); }
; DI float wave_sum(float v) {
; #pragma unroll
;   for (int o = 32; o > 0; o >>= 1) v += __shfl_xor(v, o);
;   return v;
; __global__ void __launch_bounds__(256, 2) fwd_kernel(Params p) {
;     ...
;         float ss = 0.f;
; #pragma unroll
;         for (int i = 0; i < 3; ++i) { const float a = bflo(wq[i]), bq = bfhi(wq[i]); ss += a * a + bq * bq; }
;         const float rq = rsqrtf(wave_sum(ss) * (1.f / 384.f) + 1e-6f);
;         float s2 = 0.f;
; #pragma unroll
;         for (int i = 0; i < 2; ++i) { const float a = bflo(wk[i]), bq = bfhi(wk[i]); s2 += a * a + bq * bq; }
;         const float rk = rsqrtf(wave_sum(s2) * (1.f / 256.f) + 1e-6f);
; #pragma unroll
;         for (int i = 0; i < 3; ++i) *(GAS unsigned*)(pr + PE_CQ + 2 * lane + 128 * i) = pk2(bflo(wq[i]) * rq * g2q[i].x, bfhi(wq[i]) * rq * g2q[i].y);
; #pragma unroll
;         for (int i = 0; i < 2; ++i) *(GAS unsigned*)(pr + PE_CKV + 2 * lane + 128 * i) = pk2(bflo(wk[i]) * rk * g2k[i].x, bfhi(wk[i]) * rk * g2k[i].y);
;         if (lat) {
; #pragma unroll
;           for (int u = 0; u < 2; ++u) {
;             const int dp = lane + 64 * u, grp = dp >> 4, i2 = (dp & 15) * 2;
;             const float xa0 = bflo(d0[u]), xa1 = bfhi(d0[u]), xb0 = bflo(d1[u]), xb1 = bfhi(d1[u]);
;             const f32x4 c4 = cd[u];
;             *(GAS unsigned*)(pr + PE_DK + grp * 64 + i2) = pk2(xa0 * c4[0] - xb0 * c4[1], xa1 * c4[2] - xb1 * c4[3]);
;             *(GAS unsigned*)(pr + PE_DK + grp * 64 + i2 + 32) = pk2(xa0 * c4[1] + xb0 * c4[0], xa1 * c4[3] + xb1 * c4[2]);
;           }
;           if (lane < 8) {
;             const float xa0 = bflo(kr0), xa1 = bfhi(kr0), xb0 = bflo(kr1), xb1 = bfhi(kr1);
;             *(GAS unsigned*)(pr + PE_KR + 2 * lane) = pk2(xa0 * ck[0] - xb0 * ck[1], xa1 * ck[2] - xb1 * ck[3]);
;             *(GAS unsigned*)(pr + PE_KR + 2 * lane + 16) = pk2(xa0 * ck[1] + xb0 * ck[0], xa1 * ck[3] + xb1 * ck[2]);
;           }
.LBB0_167:
	s_waitcnt vmcnt(0)
	v_readlane_b32 s16, v251, 60
	v_readlane_b32 s17, v251, 61
	s_nop 3
	v_lshl_add_u64 v[236:237], v[24:25], 0, s[16:17]
	v_add_co_u32_e32 v236, vcc, 0xe960000, v236
	s_nop 1
	v_addc_co_u32_e32 v237, vcc, 0, v237, vcc
	global_load_dword v238, v[236:237], off offset:1536
	global_load_dword v239, v[236:237], off offset:1792
	global_load_dword v240, v[236:237], off offset:2048
	global_load_dword v241, v[236:237], off offset:2304
	global_load_dword v242, v[236:237], off offset:2560
	v_and_b32_e32 v57, 0xffff0000, v44
	v_and_b32_e32 v59, 0xffff0000, v42
	v_lshlrev_b32_e32 v56, 16, v44
	v_lshlrev_b32_e32 v44, 16, v43
	v_and_b32_e32 v45, 0xffff0000, v43
	v_lshlrev_b32_e32 v58, 16, v42
	v_and_b32_e32 v43, 0xffff0000, v41
	v_and_b32_e32 v61, 0xffff0000, v40
	v_mov_b32_e32 v64, v57
	v_mov_b32_e32 v65, v59
	v_lshlrev_b32_e32 v42, 16, v41
	v_lshlrev_b32_e32 v60, 16, v40
	v_mul_f32_e32 v40, v45, v45
	v_mov_b32_e32 v62, v56
	v_mov_b32_e32 v63, v58
	v_pk_mul_f32 v[64:65], v[64:65], v[64:65]
	v_mov_b32_e32 v66, v43
	v_mov_b32_e32 v67, v61
	v_pk_fma_f32 v[40:41], v[44:45], v[44:45], v[40:41] op_sel_hi:[1,1,0]
	v_pk_fma_f32 v[62:63], v[62:63], v[62:63], v[64:65]
	v_mov_b32_e32 v64, v42
	v_mov_b32_e32 v65, v60
	v_pk_mul_f32 v[66:67], v[66:67], v[66:67]
	v_pk_add_f32 v[40:41], v[62:63], v[40:41]
	v_pk_fma_f32 v[64:65], v[64:65], v[64:65], v[66:67]
	v_mov_b32_e32 v67, v40
	v_mov_b32_e32 v66, v64
	v_mov_b32_e32 v62, v65
	v_pk_add_f32 v[40:41], v[66:67], v[62:63]
	v_mov_b32_e32 v62, v40
	v_mov_b32_e32 v63, v41
	s_mov_b64 s[10:11], 0xe960600
	v_lshl_add_u64 v[64:65], v[24:25], 0, s[10:11]
	s_mov_b32 s10, 0x3b800000
	s_mov_b32 s11, 0x3b2aaaab
	s_nop 1
	v_permlane32_swap_b32_e32 v62, v40
	v_permlane32_swap_b32_e32 v63, v41
	v_add_f32_e32 v40, v40, v62
	v_add_f32_e32 v41, v41, v63
	v_mov_b32_e32 v62, v40
	v_mov_b32_e32 v63, v41
	s_mov_b64 s[16:17], 0xe960700
	v_lshl_add_u64 v[66:67], v[24:25], 0, s[16:17]
	s_mov_b64 s[16:17], 0xe960800
	v_lshl_add_u64 v[68:69], v[24:25], 0, s[16:17]
	s_nop 1
	v_permlane16_swap_b32_e32 v62, v40
	v_permlane16_swap_b32_e32 v63, v41
	v_add_f32_e32 v40, v40, v62
	v_add_f32_e32 v41, v41, v63
	s_mov_b64 s[16:17], 0xe960900
	s_nop 1
	v_add_f32_dpp v40, v40, v40 row_ror:8 row_mask:0xf bank_mask:0xf
	v_add_f32_dpp v41, v41, v41 row_ror:8 row_mask:0xf bank_mask:0xf
	s_nop 1
	v_mov_b32_dpp v62, v40 row_shl:4 row_mask:0xf bank_mask:0x5
	v_mov_b32_dpp v63, v41 row_shl:4 row_mask:0xf bank_mask:0x5
	v_mov_b32_dpp v62, v40 row_shr:4 row_mask:0xf bank_mask:0xa
	v_mov_b32_dpp v63, v41 row_shr:4 row_mask:0xf bank_mask:0xa
	v_add_f32_e32 v40, v40, v62
	v_add_f32_e32 v41, v41, v63
	s_nop 1
	v_add_f32_dpp v40, v40, v40 quad_perm:[2,3,0,1] row_mask:0xf bank_mask:0xf
	v_add_f32_dpp v41, v41, v41 quad_perm:[2,3,0,1] row_mask:0xf bank_mask:0xf
	s_nop 1
	v_add_f32_dpp v40, v40, v40 quad_perm:[1,0,3,2] row_mask:0xf bank_mask:0xf
	v_add_f32_dpp v41, v41, v41 quad_perm:[1,0,3,2] row_mask:0xf bank_mask:0xf
	s_nop 0
	v_pk_fma_f32 v[40:41], v[40:41], s[10:11], v[186:187] op_sel_hi:[1,1,0]
	s_mov_b32 s10, 0x800000
	v_mul_f32_e32 v62, 0x4b800000, v41
	v_mul_f32_e32 v63, 0x4b800000, v40
	v_cmp_gt_f32_e32 vcc, s10, v41
	v_cmp_gt_f32_e64 s[42:43], s10, v40
	s_mov_b64 s[10:11], 0xe960a00
	v_cndmask_b32_e32 v41, v41, v62, vcc
	v_cndmask_b32_e64 v40, v40, v63, s[42:43]
	v_rsq_f32_e32 v70, v41
	v_rsq_f32_e32 v71, v40
	v_lshl_add_u64 v[40:41], v[24:25], 0, s[16:17]
	v_lshl_add_u64 v[62:63], v[24:25], 0, s[10:11]
	v_mul_f32_e32 v72, 0x45800000, v70
	v_mul_f32_e32 v73, 0x45800000, v71
	v_cndmask_b32_e32 v70, v70, v72, vcc
	v_cndmask_b32_e64 v72, v71, v73, s[42:43]
	v_pk_mul_f32 v[56:57], v[70:71], v[56:57] op_sel_hi:[0,1]
	v_pk_mul_f32 v[42:43], v[72:73], v[42:43] op_sel_hi:[0,1]
	v_pk_mul_f32 v[44:45], v[70:71], v[44:45] op_sel_hi:[0,1]
	v_pk_mul_f32 v[58:59], v[70:71], v[58:59] op_sel_hi:[0,1]
	v_pk_mul_f32 v[46:47], v[226:227], v[56:57]
	v_pk_mul_f32 v[42:43], v[232:233], v[42:43]
	v_pk_mul_f32 v[44:45], v[228:229], v[44:45]
	v_pk_mul_f32 v[48:49], v[230:231], v[58:59]
	v_cvt_pk_bf16_f32 v46, v46, v47
	v_cvt_pk_bf16_f32 v42, v42, v43
	v_cvt_pk_bf16_f32 v44, v44, v45
	v_cvt_pk_bf16_f32 v45, v48, v49
	global_store_dword v[64:65], v46, off
	global_store_dword v[66:67], v44, off
	global_store_dword v[68:69], v45, off
	global_store_dword v[40:41], v42, off
	v_pk_mul_f32 v[40:41], v[72:73], v[60:61] op_sel_hi:[0,1]
	v_pk_mul_f32 v[40:41], v[234:235], v[40:41]
	s_andn2_b64 vcc, exec, s[14:15]
	v_cvt_pk_bf16_f32 v40, v40, v41
	global_store_dword v[62:63], v40, off
	s_cbranch_vccnz .LBB0_161
	v_lshlrev_b32_e32 v42, 16, v28
	v_and_b32_e32 v43, 0xffff0000, v28
	v_mov_b32_e32 v46, v3
	v_mov_b32_e32 v47, v5
	v_lshlrev_b32_e32 v40, 16, v30
	v_and_b32_e32 v41, 0xffff0000, v30
	v_mov_b32_e32 v44, v2
	v_mov_b32_e32 v45, v4
	v_pk_mul_f32 v[48:49], v[46:47], v[42:43]
	s_mov_b32 s10, 0xe960000
	v_pk_fma_f32 v[48:49], v[44:45], v[40:41], v[48:49] neg_lo:[0,0,1] neg_hi:[0,0,1]
	v_pk_mul_f32 v[42:43], v[44:45], v[42:43]
	v_cvt_pk_bf16_f32 v50, v48, v49
	v_add_co_u32_e32 v48, vcc, s10, v26
	v_pk_fma_f32 v[40:41], v[46:47], v[40:41], v[42:43]
	s_nop 0
	v_addc_co_u32_e32 v49, vcc, 0, v27, vcc
	v_cvt_pk_bf16_f32 v40, v40, v41
	v_lshlrev_b32_e32 v42, 16, v29
	v_and_b32_e32 v43, 0xffff0000, v29
	v_mov_b32_e32 v44, v6
	v_mov_b32_e32 v45, v8
	v_mov_b32_e32 v46, v7
	v_mov_b32_e32 v47, v9
	global_store_dword v[48:49], v50, off offset:3840
	global_store_dword v[48:49], v40, off offset:3904
	v_lshlrev_b32_e32 v40, 16, v31
	v_and_b32_e32 v41, 0xffff0000, v31
	v_pk_mul_f32 v[48:49], v[46:47], v[42:43]
	v_pk_mul_f32 v[42:43], v[44:45], v[42:43]
	v_pk_fma_f32 v[48:49], v[44:45], v[40:41], v[48:49] neg_lo:[0,0,1] neg_hi:[0,0,1]
	v_add_co_u32_e32 v26, vcc, 0xe961000, v26
	v_pk_fma_f32 v[40:41], v[46:47], v[40:41], v[42:43]
	v_cvt_pk_bf16_f32 v48, v48, v49
	v_addc_co_u32_e32 v27, vcc, 0, v27, vcc
	v_cvt_pk_bf16_f32 v40, v40, v41
	global_store_dword v[26:27], v48, off offset:256
	global_store_dword v[26:27], v40, off offset:320
	s_and_saveexec_b64 s[14:15], s[40:41]
	s_cbranch_execz .LBB0_160
	v_lshlrev_b32_e32 v26, 16, v39
	v_and_b32_e32 v27, 0xffff0000, v39
	v_lshlrev_b32_e32 v40, 16, v38
	v_and_b32_e32 v41, 0xffff0000, v38
	v_mov_b32_e32 v39, v12
	v_mov_b32_e32 v12, v11
	v_mov_b32_e32 v38, v10
	v_pk_mul_f32 v[10:11], v[12:13], v[40:41]
	v_pk_mul_f32 v[12:13], v[12:13], v[26:27]
	v_pk_fma_f32 v[10:11], v[38:39], v[26:27], v[10:11] neg_lo:[0,0,1] neg_hi:[0,0,1]
	v_pk_fma_f32 v[12:13], v[38:39], v[40:41], v[12:13]
	v_cvt_pk_bf16_f32 v42, v10, v11
	v_add_co_u32_e32 v10, vcc, 0xe961000, v24
	v_cvt_pk_bf16_f32 v12, v12, v13
	s_nop 0
	v_addc_co_u32_e32 v11, vcc, 0, v25, vcc
	global_store_dword v[10:11], v42, off offset:1792
	global_store_dword v[10:11], v12, off offset:1824
	s_branch .LBB0_160
